# gate/up weight transpose loop counted waits: current item processed without waiting on the next item's just-issued loads; the next item is waited for at the latch (vmcnt(4))
# speedup vs baseline: 1.0062x; 1.0062x over previous
.Lguw_entry:
	s_waitcnt vmcnt(0)
	v_ashrrev_i32_e32 v69, 5, v66
	s_lshl_b32 s0, s72, 14
	s_movk_i32 s5, 0x2c00
	v_add_u32_e32 v16, 2, v69
	v_add_u32_e32 v18, 4, v69
	v_add_u32_e32 v20, 6, v69
	v_add_u32_e32 v22, 8, v69
	s_add_i32 s4, s0, 0
	v_mad_i64_i32 v[2:3], s[0:1], v69, s5, 0
	v_mad_i64_i32 v[4:5], s[0:1], v16, s5, 0
	v_mad_i64_i32 v[6:7], s[0:1], v18, s5, 0
	v_mad_i64_i32 v[8:9], s[0:1], v20, s5, 0
	v_mad_i64_i32 v[10:11], s[0:1], v22, s5, 0
	s_mul_hi_i32 s0, s80, 0x2e8ba2e9
	s_lshr_b32 s1, s0, 31
	s_ashr_i32 s0, s0, 9
	s_add_i32 s9, s0, s1
	s_mul_i32 s0, s9, 0xb00
	s_sub_i32 s8, s80, s0
	s_cmpk_gt_i32 s8, 0x57f
	s_cselect_b64 s[6:7], -1, 0
	s_add_i32 s10, s8, 0xfa80
	s_and_b64 s[0:1], s[6:7], exec
	s_cselect_b32 s0, s10, s8
	s_sext_i32_i16 s1, s0
	s_mulk_i32 s1, 0xba3
	s_lshr_b32 s8, s1, 31
	s_ashr_i32 s1, s1, 18
	s_add_i32 s10, s1, s8
	s_mul_i32 s1, s10, 0x58
	s_sub_i32 s0, s0, s1
	s_sext_i32_i16 s0, s0
	s_lshl_b32 s1, s0, 6
	s_and_b32 s1, s1, 0xffffff00
	s_mul_i32 s8, s9, 0x1600
	s_add_i32 s1, s1, s8
	s_lshl_b32 s8, s0, 5
	s_and_b32 s0, s8, 0x60
	s_or_b32 s11, s1, s0
	s_and_b64 s[0:1], s[6:7], exec
	s_cselect_b32 s0, 0x80, 0
	s_or_b32 s0, s11, s0
	s_ashr_i32 s1, s0, 31
	s_lshl_b64 s[0:1], s[0:1], 10
	s_add_u32 s0, s88, s0
	s_sext_i32_i16 s10, s10
	s_addc_u32 s1, s89, s1
	s_lshl_b32 s11, s10, 6
	s_ashr_i32 s12, s11, 31
	s_add_u32 s0, s0, s11
	s_addc_u32 s1, s1, s12
	v_readlane_b32 s12, v253, 18
	v_readlane_b32 s13, v253, 19
	v_readlane_b32 s14, v253, 20
	v_readlane_b32 s15, v253, 21
	v_readlane_b32 s16, v253, 22
	v_readlane_b32 s17, v253, 23
	v_readlane_b32 s18, v253, 24
	v_readlane_b32 s19, v253, 25
	v_readlane_b32 s20, v253, 26
	v_readlane_b32 s21, v253, 27
	v_readlane_b32 s22, v253, 28
	v_readlane_b32 s23, v253, 29
	v_readlane_b32 s24, v253, 30
	v_readlane_b32 s25, v253, 31
	v_readlane_b32 s26, v253, 32
	v_readlane_b32 s27, v253, 33
	s_mov_b64 s[12:13], s[16:17]
	s_and_b64 s[6:7], s[6:7], exec
	s_mov_b64 s[14:15], s[18:19]
	s_mov_b64 s[16:17], s[20:21]
	s_mov_b64 s[18:19], s[22:23]
	s_mov_b64 s[20:21], s[24:25]
	s_cselect_b32 s7, s20, s18
	s_mul_hi_i32 s12, s9, 0xb00000
	s_mul_i32 s9, s9, 0xb00000
	s_cselect_b32 s6, s21, s19
	s_add_u32 s7, s7, s9
	s_addc_u32 s6, s6, s12
	s_mul_i32 s10, s10, 0xb0000
	s_mul_hi_i32 s9, s11, 0x2c00
	s_add_u32 s10, s7, s10
	s_addc_u32 s11, s6, s9
	s_ashr_i32 s9, s8, 31
	s_lshl_b64 s[6:7], s[8:9], 2
	v_and_b32_e32 v76, 31, v66
	s_add_u32 s6, s10, s6
	v_mov_b32_e32 v1, 0
	s_addc_u32 s7, s11, s7
	v_lshlrev_b32_e32 v0, 2, v76
	v_lshl_add_u64 v[12:13], s[6:7], 0, v[0:1]
	v_add_u32_e32 v30, 10, v69
	v_add_u32_e32 v31, 12, v69
	v_add_u32_e32 v32, 14, v69
	v_add_u32_e32 v33, 16, v69
	v_mad_i64_i32 v[14:15], s[6:7], v69, s5, v[12:13]
	v_add_u32_e32 v34, 18, v69
	v_add_u32_e32 v35, 20, v69
	v_add_u32_e32 v36, 22, v69
	v_add_u32_e32 v37, 24, v69
	v_add_u32_e32 v38, 26, v69
	v_add_u32_e32 v39, 28, v69
	v_add_u32_e32 v40, 30, v69
	v_add_u32_e32 v41, 32, v69
	v_mad_i64_i32 v[16:17], s[6:7], v16, s5, v[12:13]
	v_mad_i64_i32 v[18:19], s[6:7], v18, s5, v[12:13]
	v_mad_i64_i32 v[20:21], s[6:7], v20, s5, v[12:13]
	v_mad_i64_i32 v[22:23], s[6:7], v22, s5, v[12:13]
	v_mad_i64_i32 v[24:25], s[6:7], v30, s5, v[12:13]
	v_mad_i64_i32 v[26:27], s[6:7], v31, s5, v[12:13]
	v_mad_i64_i32 v[28:29], s[6:7], v32, s5, v[12:13]
	global_load_dword v78, v[14:15], off
	global_load_dword v79, v[16:17], off
	global_load_dword v80, v[18:19], off
	global_load_dword v81, v[20:21], off
	global_load_dword v82, v[22:23], off
	global_load_dword v84, v[24:25], off
	global_load_dword v83, v[26:27], off
	global_load_dword v85, v[28:29], off
	v_mad_i64_i32 v[14:15], s[6:7], v33, s5, v[12:13]
	v_add_u32_e32 v42, 34, v69
	v_add_u32_e32 v43, 36, v69
	v_add_u32_e32 v44, 38, v69
	v_add_u32_e32 v45, 40, v69
	v_add_u32_e32 v46, 42, v69
	v_add_u32_e32 v47, 44, v69
	v_add_u32_e32 v48, 46, v69
	v_add_u32_e32 v50, 48, v69
	v_mad_i64_i32 v[16:17], s[6:7], v34, s5, v[12:13]
	v_mad_i64_i32 v[18:19], s[6:7], v35, s5, v[12:13]
	v_mad_i64_i32 v[20:21], s[6:7], v36, s5, v[12:13]
	v_mad_i64_i32 v[22:23], s[6:7], v37, s5, v[12:13]
	v_mad_i64_i32 v[24:25], s[6:7], v38, s5, v[12:13]
	v_mad_i64_i32 v[26:27], s[6:7], v39, s5, v[12:13]
	v_mad_i64_i32 v[28:29], s[6:7], v40, s5, v[12:13]
	global_load_dword v86, v[14:15], off
	global_load_dword v88, v[16:17], off
	global_load_dword v87, v[18:19], off
	global_load_dword v89, v[20:21], off
	global_load_dword v90, v[22:23], off
	global_load_dword v92, v[24:25], off
	global_load_dword v91, v[26:27], off
	global_load_dword v93, v[28:29], off
	v_mad_i64_i32 v[14:15], s[6:7], v41, s5, v[12:13]
	v_add_u32_e32 v52, 50, v69
	v_add_u32_e32 v54, 52, v69
	v_add_u32_e32 v56, 54, v69
	v_add_u32_e32 v58, 56, v69
	v_add_u32_e32 v60, 58, v69
	v_add_u32_e32 v62, 60, v69
	v_add_u32_e32 v64, 62, v69
	v_mad_i64_i32 v[16:17], s[6:7], v42, s5, v[12:13]
	v_mad_i64_i32 v[18:19], s[6:7], v43, s5, v[12:13]
	v_mad_i64_i32 v[20:21], s[6:7], v44, s5, v[12:13]
	v_mad_i64_i32 v[22:23], s[6:7], v45, s5, v[12:13]
	v_mad_i64_i32 v[24:25], s[6:7], v46, s5, v[12:13]
	v_mad_i64_i32 v[26:27], s[6:7], v47, s5, v[12:13]
	v_mad_i64_i32 v[28:29], s[6:7], v48, s5, v[12:13]
	global_load_dword v94, v[14:15], off
	global_load_dword v96, v[16:17], off
	global_load_dword v95, v[18:19], off
	global_load_dword v97, v[20:21], off
	global_load_dword v98, v[22:23], off
	global_load_dword v100, v[24:25], off
	global_load_dword v99, v[26:27], off
	global_load_dword v101, v[28:29], off
	v_mad_i64_i32 v[14:15], s[6:7], v50, s5, v[12:13]
	v_mad_i64_i32 v[16:17], s[6:7], v52, s5, v[12:13]
	v_mad_i64_i32 v[18:19], s[6:7], v54, s5, v[12:13]
	v_mad_i64_i32 v[20:21], s[6:7], v56, s5, v[12:13]
	v_mad_i64_i32 v[22:23], s[6:7], v58, s5, v[12:13]
	v_mad_i64_i32 v[24:25], s[6:7], v60, s5, v[12:13]
	v_mad_i64_i32 v[26:27], s[6:7], v62, s5, v[12:13]
	v_mad_i64_i32 v[12:13], s[6:7], v64, s5, v[12:13]
	global_load_dword v102, v[14:15], off
	global_load_dword v104, v[16:17], off
	global_load_dword v103, v[18:19], off
	global_load_dword v105, v[20:21], off
	global_load_dword v106, v[22:23], off
	global_load_dword v108, v[24:25], off
	global_load_dword v107, v[26:27], off
	global_load_dword v109, v[12:13], off
	v_add_u32_e32 v110, s4, v0
	v_lshlrev_b32_e32 v0, 3, v66
	v_mad_i64_i32 v[12:13], s[6:7], v30, s5, 0
	v_mad_i64_i32 v[14:15], s[6:7], v31, s5, 0
	v_mad_i64_i32 v[16:17], s[6:7], v32, s5, 0
	v_mad_i64_i32 v[18:19], s[6:7], v33, s5, 0
	v_mad_i64_i32 v[20:21], s[6:7], v34, s5, 0
	v_mad_i64_i32 v[22:23], s[6:7], v35, s5, 0
	v_mad_i64_i32 v[24:25], s[6:7], v36, s5, 0
	v_mad_i64_i32 v[26:27], s[6:7], v37, s5, 0
	v_mad_i64_i32 v[28:29], s[6:7], v38, s5, 0
	v_mad_i64_i32 v[30:31], s[6:7], v39, s5, 0
	v_mad_i64_i32 v[32:33], s[6:7], v40, s5, 0
	v_mad_i64_i32 v[34:35], s[6:7], v41, s5, 0
	v_mad_i64_i32 v[36:37], s[6:7], v42, s5, 0
	v_mad_i64_i32 v[38:39], s[6:7], v43, s5, 0
	v_mad_i64_i32 v[40:41], s[6:7], v44, s5, 0
	v_mad_i64_i32 v[42:43], s[6:7], v45, s5, 0
	v_mad_i64_i32 v[44:45], s[6:7], v46, s5, 0
	v_mad_i64_i32 v[46:47], s[6:7], v47, s5, 0
	v_mad_i64_i32 v[48:49], s[6:7], v48, s5, 0
	v_mad_i64_i32 v[50:51], s[6:7], v50, s5, 0
	v_mad_i64_i32 v[52:53], s[6:7], v52, s5, 0
	v_mad_i64_i32 v[54:55], s[6:7], v54, s5, 0
	v_mad_i64_i32 v[56:57], s[6:7], v56, s5, 0
	v_mad_i64_i32 v[58:59], s[6:7], v58, s5, 0
	v_mad_i64_i32 v[60:61], s[6:7], v60, s5, 0
	v_mad_i64_i32 v[62:63], s[6:7], v62, s5, 0
	v_mad_i64_i32 v[64:65], s[6:7], v64, s5, 0
	v_ashrrev_i32_e32 v68, 3, v66
	v_and_b32_e32 v66, 56, v0
	s_movk_i32 s5, 0x84
	v_mul_u32_u24_e32 v0, 0x84, v66
	v_mul_lo_u32 v111, v69, s5
	v_lshlrev_b32_e32 v69, 2, v68
	v_add3_u32 v77, s4, v0, v69
	v_ashrrev_i32_e32 v69, 31, v68
	v_lshlrev_b64 v[68:69], 10, v[68:69]
	s_mov_b64 s[4:5], 0x2000
	v_lshl_add_u64 v[70:71], v[68:69], 0, s[4:5]
	s_mov_b64 s[4:5], 0x4000
	v_lshl_add_u64 v[72:73], v[68:69], 0, s[4:5]
	s_mov_b64 s[4:5], 0x6000
	v_mov_b32_e32 v67, v1
	v_lshl_add_u64 v[74:75], v[68:69], 0, s[4:5]
	v_lshlrev_b32_e32 v0, 2, v76
	v_add_u32_e32 v76, v110, v111
	s_mov_b32 s8, s80
	s_mov_b64 s[4:5], s[0:1]
	s_mov_b64 s[22:23], s[26:27]
	s_waitcnt vmcnt(0)
	s_branch .LBB0_710
.LBB0_709:
	v_mul_f32_e32 v78, 0x42000000, v78
	v_mul_f32_e32 v79, 0x42000000, v79
	ds_write2_b32 v76, v78, v79 offset1:66
	v_mul_f32_e32 v78, 0x42000000, v80
	v_mul_f32_e32 v79, 0x42000000, v81
	ds_write2_b32 v76, v78, v79 offset0:132 offset1:198
	v_mul_f32_e32 v78, 0x42000000, v82
	v_mul_f32_e32 v79, 0x42000000, v84
	v_add_u32_e32 v80, 0x400, v76
	ds_write2_b32 v80, v78, v79 offset0:8 offset1:74
	v_mul_f32_e32 v78, 0x42000000, v83
	v_mul_f32_e32 v79, 0x42000000, v85
	ds_write2_b32 v80, v78, v79 offset0:140 offset1:206
	v_mul_f32_e32 v78, 0x42000000, v86
	v_mul_f32_e32 v79, 0x42000000, v88
	v_add_u32_e32 v80, 0x800, v76
	ds_write2_b32 v80, v78, v79 offset0:16 offset1:82
	v_mul_f32_e32 v78, 0x42000000, v87
	v_mul_f32_e32 v79, 0x42000000, v89
	ds_write2_b32 v80, v78, v79 offset0:148 offset1:214
	v_mul_f32_e32 v78, 0x42000000, v90
	v_mul_f32_e32 v79, 0x42000000, v92
	v_add_u32_e32 v80, 0xc00, v76
	ds_write2_b32 v80, v78, v79 offset0:24 offset1:90
	v_mul_f32_e32 v78, 0x42000000, v91
	v_mul_f32_e32 v79, 0x42000000, v93
	ds_write2_b32 v80, v78, v79 offset0:156 offset1:222
	v_mul_f32_e32 v78, 0x42000000, v94
	v_mul_f32_e32 v79, 0x42000000, v96
	v_add_u32_e32 v80, 0x1000, v76
	ds_write2_b32 v80, v78, v79 offset0:32 offset1:98
	v_mul_f32_e32 v78, 0x42000000, v95
	v_mul_f32_e32 v79, 0x42000000, v97
	ds_write2_b32 v80, v78, v79 offset0:164 offset1:230
	v_mul_f32_e32 v78, 0x42000000, v98
	v_mul_f32_e32 v79, 0x42000000, v100
	v_add_u32_e32 v80, 0x1400, v76
	ds_write2_b32 v80, v78, v79 offset0:40 offset1:106
	v_mul_f32_e32 v78, 0x42000000, v99
	v_mul_f32_e32 v79, 0x42000000, v101
	ds_write2_b32 v80, v78, v79 offset0:172 offset1:238
	v_mul_f32_e32 v78, 0x42000000, v102
	v_mul_f32_e32 v79, 0x42000000, v104
	v_add_u32_e32 v80, 0x1800, v76
	ds_write2_b32 v80, v78, v79 offset0:48 offset1:114
	v_mul_f32_e32 v78, 0x42000000, v103
	v_mul_f32_e32 v79, 0x42000000, v105
	ds_write2_b32 v80, v78, v79 offset0:180 offset1:246
	v_mul_f32_e32 v78, 0x42000000, v106
	v_mul_f32_e32 v79, 0x42000000, v108
	v_add_u32_e32 v80, 0x1c00, v76
	ds_write2_b32 v80, v78, v79 offset0:56 offset1:122
	v_mul_f32_e32 v78, 0x42000000, v107
	v_mul_f32_e32 v79, 0x42000000, v109
	ds_write2_b32 v80, v78, v79 offset0:188 offset1:254
	s_waitcnt lgkmcnt(0)
	ds_read2_b32 v[80:81], v77 offset0:33 offset1:41
	ds_read2_b32 v[82:83], v77 offset0:66 offset1:74
	ds_read2_b32 v[84:85], v77 offset1:8
	ds_read2_b32 v[86:87], v77 offset0:99 offset1:107
	ds_read2_b32 v[90:91], v77 offset0:132 offset1:140
	ds_read2_b32 v[92:93], v77 offset0:165 offset1:173
	v_mov_b32_e32 v88, 0
	ds_read2_b32 v[94:95], v77 offset0:198 offset1:206
	ds_read2_b32 v[96:97], v77 offset0:231 offset1:239
	s_waitcnt lgkmcnt(5)
	v_cvt_pk_fp8_f32 v88, v84, v80
	v_mov_b32_e32 v89, 0
	v_mov_b32_e32 v80, 0
	s_waitcnt lgkmcnt(2)
	v_cvt_pk_fp8_f32 v89, v90, v92
	v_cvt_pk_fp8_f32 v80, v85, v81
	v_mov_b32_e32 v81, 0
	v_cvt_pk_fp8_f32 v81, v91, v93
	v_cvt_pk_fp8_f32 v88, v82, v86 op_sel:[0,0,1]
	s_waitcnt lgkmcnt(0)
	v_cvt_pk_fp8_f32 v89, v94, v96 op_sel:[0,0,1]
	v_cvt_pk_fp8_f32 v80, v83, v87 op_sel:[0,0,1]
	v_cvt_pk_fp8_f32 v81, v95, v97 op_sel:[0,0,1]
	v_lshl_add_u64 v[78:79], s[0:1], 0, v[66:67]
	v_lshl_add_u64 v[82:83], v[78:79], 0, v[68:69]
	global_store_dwordx2 v[82:83], v[88:89], off
	v_lshl_add_u64 v[82:83], v[78:79], 0, v[70:71]
	global_store_dwordx2 v[82:83], v[80:81], off
	ds_read2_b32 v[80:81], v77 offset0:49 offset1:57
	ds_read2_b32 v[82:83], v77 offset0:82 offset1:90
	ds_read2_b32 v[84:85], v77 offset0:16 offset1:24
	ds_read2_b32 v[86:87], v77 offset0:115 offset1:123
	ds_read2_b32 v[90:91], v77 offset0:148 offset1:156
	ds_read2_b32 v[92:93], v77 offset0:181 offset1:189
	v_mov_b32_e32 v88, 0
	ds_read2_b32 v[94:95], v77 offset0:214 offset1:222
	ds_read2_b32 v[96:97], v77 offset0:247 offset1:255
	s_waitcnt lgkmcnt(5)
	v_cvt_pk_fp8_f32 v88, v84, v80
	v_mov_b32_e32 v80, 0
	v_mov_b32_e32 v89, 0
	v_cvt_pk_fp8_f32 v80, v85, v81
	v_mov_b32_e32 v81, 0
	s_waitcnt lgkmcnt(2)
	v_cvt_pk_fp8_f32 v89, v90, v92
	v_cvt_pk_fp8_f32 v81, v91, v93
	v_cvt_pk_fp8_f32 v88, v82, v86 op_sel:[0,0,1]
	v_cvt_pk_fp8_f32 v80, v83, v87 op_sel:[0,0,1]
	s_waitcnt lgkmcnt(0)
	v_cvt_pk_fp8_f32 v89, v94, v96 op_sel:[0,0,1]
	v_cvt_pk_fp8_f32 v81, v95, v97 op_sel:[0,0,1]
	v_lshl_add_u64 v[82:83], v[78:79], 0, v[72:73]
	v_lshl_add_u64 v[78:79], v[78:79], 0, v[74:75]
	global_store_dwordx2 v[82:83], v[88:89], off
	global_store_dwordx2 v[78:79], v[80:81], off
	s_waitcnt lgkmcnt(0)
	s_andn2_b64 vcc, exec, s[6:7]
	s_mov_b64 s[0:1], s[4:5]
	s_waitcnt vmcnt(4)
	v_mov_b32_e32 v78, v117
	v_mov_b32_e32 v79, v116
	v_mov_b32_e32 v80, v115
	v_mov_b32_e32 v81, v114
	v_mov_b32_e32 v82, v113
	v_mov_b32_e32 v84, v112
	v_mov_b32_e32 v83, v111
	v_mov_b32_e32 v85, v110
	v_mov_b32_e32 v86, v125
	v_mov_b32_e32 v88, v124
	v_mov_b32_e32 v87, v123
	v_mov_b32_e32 v89, v122
	v_mov_b32_e32 v90, v121
	v_mov_b32_e32 v92, v120
	v_mov_b32_e32 v91, v119
	v_mov_b32_e32 v93, v118
	v_mov_b32_e32 v94, v133
	v_mov_b32_e32 v96, v132
	v_mov_b32_e32 v95, v131
	v_mov_b32_e32 v97, v130
	v_mov_b32_e32 v98, v129
	v_mov_b32_e32 v100, v128
	v_mov_b32_e32 v99, v127
	v_mov_b32_e32 v101, v126
	v_mov_b32_e32 v102, v141
	v_mov_b32_e32 v104, v140
	v_mov_b32_e32 v103, v139
	v_mov_b32_e32 v105, v138
	v_mov_b32_e32 v106, v137
	v_mov_b32_e32 v108, v136
	v_mov_b32_e32 v107, v135
	v_mov_b32_e32 v109, v134
	s_cbranch_vccz .LBB0_712
